# s5_c GLU segment rewritten: each wave owns 2 feature tiles x 64 tokens, table fragments loaded once and issued at scan start, token fragments double-buffered from LDS
# speedup vs baseline: 1.0732x; 1.0119x over previous
; #define LAS __attribute__((address_space(3)))
; __device__ __forceinline__ int tidx() { int t = threadIdx.x; asm volatile("" : "+v"(t)); return t; }
; #define LBAR() do { asm volatile("s_waitcnt lgkmcnt(0)" ::: "memory"); __builtin_amdgcn_s_barrier(); asm volatile("" ::: "memory"); } while (0)
; __device__ __forceinline__ void s5_load_u(LAS bf16_t* UB, KP& P_, int bc) {
;     const bf16_t* proj = (const bf16_t*)(p.ws + WS_PROJ);
;     for (int it = 0; it < 4; ++it) { const int item = it * NTHR + tidx(), t = item >> 5, c8 = (item & 31) * 8;
;         *(LAS u32x4*)(UB + t * 264 + c8) = *(const u32x4*)(proj + ((size_t)bc * 64 + t) * NPROJ + C_U + c8); }
; }
; __device__ void s5_a_unit(LAS unsigned char* lds, KP& P_, int l, int bc) {
;     LAS bf16_t* UB = (LAS bf16_t*)lds; LAS bf16_t* XB = (LAS bf16_t*)(lds + 33792);
;     const int tid = tidx(), wid = tid >> 6, lane = tid & 63, fr = lane & 15, fq = lane >> 4;
;     s5_load_u(UB, P_, bc);
;     LBAR();
; __device__ void s5_c_unit(LAS unsigned char* lds, KP& P_, int l, int bc) {
;     ...
;         const bf16_t* glut = (const bf16_t*)(p.ws + TBL(T_GLUT, l)); const float* gb = p.in[20] + l * 256; bf16_t* mixed = (bf16_t*)(p.ws + WS_MIXED);
;         bf16x8 gn[8]; f32x4 gbv[8];
; #pragma unroll
;         for (int i = 0; i < 8; ++i) gbv[i] = *(const f32x4*)(gb + (jh * 8 + i) * 16 + fq * 4);
; #pragma unroll
;         for (int ks = 0; ks < 8; ++ks) gn[ks] = *(const bf16x8*)(glut + (size_t)(jh * 128 + fr) * 256 + ks * 32 + fq * 8);
.LBB0_314:
	s_or_b64 exec, exec, s[6:7]
	v_readlane_b32 s6, v255, 25
	v_readlane_b32 s7, v255, 26
	s_mov_b32 s13, s6
	s_mov_b64 s[24:25], s[30:31]
	s_cmpk_gt_i32 s20, 0x207
	s_mov_b64 s[6:7], -1
	s_cbranch_scc0 .LBB0_340
	s_waitcnt vmcnt(3)
	v_mov_b32_e32 v60, v198
	s_load_dwordx2 s[6:7], s[24:25], 0xe8
	v_mov_b32_e32 v0, v198
	s_add_i32 s22, s20, 0xfffffdf8
	s_lshl_b32 s90, s22, 6
	v_ashrrev_i32_e32 v2, 5, v0
	v_ashrrev_i32_e32 v3, 31, v2
	v_lshl_add_u64 v[8:9], v[2:3], 0, s[90:91]
	s_waitcnt lgkmcnt(0)
	v_mov_b64_e32 v[12:13], s[6:7]
	v_mad_u64_u32 v[10:11], s[14:15], v8, s9, v[12:13]
	v_lshlrev_b32_e32 v0, 4, v0
	v_mad_i32_i24 v11, v9, s9, v11
	v_and_b32_e32 v0, 0x1f0, v0
	v_lshl_add_u64 v[8:9], v[10:11], 0, v[0:1]
	s_movk_i32 s12, 0x1000
	v_add_co_u32_e32 v8, vcc, s12, v8
	s_movk_i32 s23, 0x210
	s_nop 0
	v_addc_co_u32_e32 v9, vcc, 0, v9, vcc
	s_mov_b64 s[14:15], 0x18000
	v_lshl_add_u64 v[20:21], v[8:9], 0, s[14:15]
	v_lshl_add_u64 v[22:23], v[20:21], 0, s[14:15]
	v_lshl_add_u64 v[24:25], v[22:23], 0, s[14:15]
	global_load_dwordx4 v[28:31], v[8:9], off offset:1536
	global_load_dwordx4 v[32:35], v[20:21], off offset:1536
	global_load_dwordx4 v[36:39], v[22:23], off offset:1536
	global_load_dwordx4 v[8:11], v[24:25], off offset:1536
	v_mul_lo_u32 v2, v2, s23
	v_add3_u32 v0, 0, v2, v0
	v_ashrrev_i32_e32 v66, 6, v60
	v_and_b32_e32 v63, 15, v60
	v_and_b32_e32 v88, 63, v60
	s_movk_i32 s26, 0x210
	v_mov_b32_e32 v14, 0
	v_mov_b32_e32 v15, 0
	v_mov_b32_e32 v16, 0
	v_mov_b32_e32 v17, 0
	v_mov_b32_e32 v18, 0
	v_mov_b32_e32 v19, 0
	s_mul_i32 s14, s13, 0x44800
	s_mul_hi_i32 s12, s13, 0x44800
	s_add_u32 s42, s6, s14
	s_addc_u32 s43, s7, s12
	s_load_dwordx2 s[62:63], s[24:25], 0xa0
	v_cmp_gt_u32_e32 vcc, 32, v88
	v_mov_b32_e32 v12, 0
	v_mov_b32_e32 v13, 0
	s_waitcnt vmcnt(3)
	ds_write_b128 v0, v[28:31]
	s_waitcnt vmcnt(2)
	ds_write_b128 v0, v[32:35] offset:8448
	s_waitcnt vmcnt(1)
	ds_write_b128 v0, v[36:39] offset:16896
	s_waitcnt vmcnt(0)
	ds_write_b128 v0, v[8:11] offset:25344
	v_and_b32_e32 v0, 16, v60
	v_lshl_add_u64 v[2:3], s[42:43], 0, v[0:1]
	v_lshl_add_u64 v[68:69], v[2:3], 0, s[80:81]
	v_lshl_or_b32 v2, v66, 7, v63
	s_waitcnt lgkmcnt(0)
	s_barrier
	s_add_u32 s64, s42, 0xef29000
	s_addc_u32 s65, s43, 0
	s_lshl_b32 s66, s13, 10
	s_add_u32 s62, s62, s66
	s_addc_u32 s63, s63, 0
	v_lshrrev_b32_e32 v134, 6, v198
	v_and_b32_e32 v141, 15, v198
	v_bfe_u32 v142, v198, 4, 2
	v_lshlrev_b32_e32 v143, 14, v134
	v_lshl_add_u32 v143, v141, 9, v143
	v_lshl_add_u32 v168, v142, 4, v143
	v_mov_b32_e32 v169, 0
	v_lshl_add_u64 v[168:169], s[64:65], 0, v[168:169]
	s_mov_b64 s[66:67], 0x2000
	v_lshl_add_u64 v[210:211], v[168:169], 0, s[66:67]
	global_load_dwordx4 v[106:109], v[168:169], off
	global_load_dwordx4 v[110:113], v[168:169], off offset:64
	global_load_dwordx4 v[114:117], v[168:169], off offset:128
	global_load_dwordx4 v[118:121], v[168:169], off offset:192
	global_load_dwordx4 v[122:125], v[168:169], off offset:256
	global_load_dwordx4 v[126:129], v[168:169], off offset:320
	global_load_dwordx4 v[130:133], v[168:169], off offset:384
	global_load_dwordx4 v[148:151], v[168:169], off offset:448
	global_load_dwordx4 v[152:155], v[210:211], off
	global_load_dwordx4 v[160:163], v[210:211], off offset:64
	global_load_dwordx4 v[164:167], v[210:211], off offset:128
	global_load_dwordx4 v[184:187], v[210:211], off offset:192
	global_load_dwordx4 v[188:191], v[210:211], off offset:256
	global_load_dwordx4 v[222:225], v[210:211], off offset:320
	global_load_dwordx4 v[226:229], v[210:211], off offset:384
	global_load_dwordx4 v[230:233], v[210:211], off offset:448
	v_lshlrev_b32_e32 v143, 7, v134
	v_lshl_add_u32 v216, v142, 4, v143
	v_mov_b32_e32 v217, 0
	v_lshl_add_u64 v[216:217], s[62:63], 0, v[216:217]
	global_load_dwordx4 v[234:237], v[216:217], off
	global_load_dwordx4 v[238:241], v[216:217], off offset:64
	v_ashrrev_i32_e32 v3, 31, v2
	v_lshlrev_b64 v[2:3], 5, v[2:3]
	v_lshl_add_u64 v[2:3], v[68:69], 0, v[2:3]
	v_mov_b32_e32 v8, 0
	s_and_saveexec_b64 s[14:15], vcc
	s_cbranch_execz .LBB0_317
	global_load_dwordx4 v[16:19], v[2:3], off
	global_load_dwordx4 v[12:15], v[2:3], off offset:512

; #define LAS __attribute__((address_space(3)))
; __device__ __forceinline__ float bflo(unsigned w) { return __uint_as_float(w << 16); }
; __device__ __forceinline__ float bfhi(unsigned w) { return __uint_as_float(w & 0xffff0000u); }
; __device__ __forceinline__ u32x2 pack4(const f32x4 a) { u32x2 v; v.x = cvt_pk_bf16(a[0], a[1]); v.y = cvt_pk_bf16(a[2], a[3]); return v; }
; __device__ __forceinline__ float sigmoidf_(float x) { return __builtin_amdgcn_rcpf(1.0f + __expf(-x)); }
; #define MFMA16(a, b, c) __builtin_amdgcn_mfma_f32_16x16x32_bf16((a), (b), (c), 0, 0, 0)
; __device__ void s5_c_unit(LAS unsigned char* lds, KP& P_, int l, int bc) {
;     ...
;         for (int i = 0; i < 8; ++i) { const int jt = jh * 8 + i; f32x4 acc = (f32x4){0.f, 0.f, 0.f, 0.f};
;             bf16x8 gc[8];
; #pragma unroll
;             for (int ks = 0; ks < 8; ++ks) gc[ks] = gn[ks];
;             if (i < 7) {
; #pragma unroll
;                 for (int ks = 0; ks < 8; ++ks) gn[ks] = *(const bf16x8*)(glut + (size_t)((jt + 1) * 16 + fr) * 256 + ks * 32 + fq * 8); }
; #pragma unroll
;             for (int ks = 0; ks < 8; ++ks) acc = MFMA16(gc[ks], yf[ks], acc);
;             const int jc = jt * 16 + fq * 4; const u32x2 yraw = *(const LAS u32x2*)(YG + tq * 264 + jc); const float yv[4] = {bflo(yraw.x), bfhi(yraw.x), bflo(yraw.y), bfhi(yraw.y)}; f32x4 r;
; #pragma unroll
;             for (int j = 0; j < 4; ++j) r[j] = yv[j] * sigmoidf_(acc[j] + gbv[i][j]);
;             *(u32x2*)(mixed + ((size_t)bc * 64 + tq) * DM + 768 + jc) = pack4(r); }
.LBB0_339:
	s_waitcnt lgkmcnt(0)
	s_barrier
	s_waitcnt vmcnt(0)
	v_and_b32_e32 v8, 15, v198
	v_bfe_u32 v9, v198, 4, 2
	v_lshrrev_b32_e32 v10, 6, v198
	v_mul_u32_u24_e32 v11, 0x210, v8
	v_add_u32_e32 v11, 0x10c00, v11
	v_lshl_add_u32 v12, v9, 4, v11
	v_lshl_add_u32 v13, v9, 3, v11
	v_lshl_add_u32 v13, v10, 6, v13
	v_lshlrev_b32_e32 v14, 11, v8
	v_lshl_add_u32 v14, v9, 3, v14
	v_lshl_add_u32 v14, v10, 6, v14
	s_lshl_b32 s12, s22, 17
	v_add_u32_e32 v14, s12, v14
	v_mov_b32_e32 v15, 0
	s_add_u32 s14, s6, 0x6180600
	s_addc_u32 s15, s7, 0
	v_lshl_add_u64 v[104:105], s[14:15], 0, v[14:15]
	s_mov_b64 s[14:15], 0x8000
	ds_read_b128 v[16:19], v12 offset:0
	ds_read_b128 v[20:23], v12 offset:64
	ds_read_b128 v[24:27], v12 offset:128
	ds_read_b128 v[28:31], v12 offset:192
	ds_read_b128 v[32:35], v12 offset:256
	ds_read_b128 v[36:39], v12 offset:320
	ds_read_b128 v[40:43], v12 offset:384
	ds_read_b128 v[44:47], v12 offset:448
	ds_read_b128 v[48:51], v12 offset:8448
	ds_read_b128 v[52:55], v12 offset:8512
	ds_read_b128 v[56:59], v12 offset:8576
	ds_read_b128 v[60:63], v12 offset:8640
	ds_read_b128 v[64:67], v12 offset:8704
	ds_read_b128 v[68:71], v12 offset:8768
	ds_read_b128 v[72:75], v12 offset:8832
	ds_read_b128 v[76:79], v12 offset:8896
	s_waitcnt lgkmcnt(8)
	v_mfma_f32_16x16x32_bf16 v[84:87], v[106:109], v[16:19], 0
	v_mfma_f32_16x16x32_bf16 v[88:91], v[152:155], v[16:19], 0
	v_mfma_f32_16x16x32_bf16 v[84:87], v[110:113], v[20:23], v[84:87]
	v_mfma_f32_16x16x32_bf16 v[88:91], v[160:163], v[20:23], v[88:91]
	v_mfma_f32_16x16x32_bf16 v[84:87], v[114:117], v[24:27], v[84:87]
	v_mfma_f32_16x16x32_bf16 v[88:91], v[164:167], v[24:27], v[88:91]
	v_mfma_f32_16x16x32_bf16 v[84:87], v[118:121], v[28:31], v[84:87]
	v_mfma_f32_16x16x32_bf16 v[88:91], v[184:187], v[28:31], v[88:91]
	v_mfma_f32_16x16x32_bf16 v[84:87], v[122:125], v[32:35], v[84:87]
	v_mfma_f32_16x16x32_bf16 v[88:91], v[188:191], v[32:35], v[88:91]
	v_mfma_f32_16x16x32_bf16 v[84:87], v[126:129], v[36:39], v[84:87]
	v_mfma_f32_16x16x32_bf16 v[88:91], v[222:225], v[36:39], v[88:91]
	v_mfma_f32_16x16x32_bf16 v[84:87], v[130:133], v[40:43], v[84:87]
	v_mfma_f32_16x16x32_bf16 v[88:91], v[226:229], v[40:43], v[88:91]
	v_mfma_f32_16x16x32_bf16 v[84:87], v[148:151], v[44:47], v[84:87]
	v_mfma_f32_16x16x32_bf16 v[88:91], v[230:233], v[44:47], v[88:91]
	ds_read_b64 v[80:81], v13 offset:0
	ds_read_b64 v[82:83], v13 offset:32
	ds_read_b128 v[16:19], v12 offset:16896
	ds_read_b128 v[20:23], v12 offset:16960
	ds_read_b128 v[24:27], v12 offset:17024
	ds_read_b128 v[28:31], v12 offset:17088
	ds_read_b128 v[32:35], v12 offset:17152
	ds_read_b128 v[36:39], v12 offset:17216
	ds_read_b128 v[40:43], v12 offset:17280
	ds_read_b128 v[44:47], v12 offset:17344
	s_waitcnt lgkmcnt(8)
	s_nop 7
	v_pk_add_f32 v[242:243], v[84:85], v[234:235]
	v_pk_add_f32 v[244:245], v[86:87], v[236:237]
	v_mul_f32_e32 v242, 0xbfb8aa3b, v242
	v_mul_f32_e32 v243, 0xbfb8aa3b, v243
	v_mul_f32_e32 v244, 0xbfb8aa3b, v244
	v_mul_f32_e32 v245, 0xbfb8aa3b, v245
	v_exp_f32_e32 v242, v242
	v_exp_f32_e32 v243, v243
	v_exp_f32_e32 v244, v244
	v_exp_f32_e32 v245, v245
	v_add_f32_e32 v242, 1.0, v242
	v_add_f32_e32 v243, 1.0, v243
	v_add_f32_e32 v244, 1.0, v244
	v_add_f32_e32 v245, 1.0, v245
	v_rcp_f32_e32 v242, v242
	v_rcp_f32_e32 v243, v243
	v_rcp_f32_e32 v244, v244
	v_rcp_f32_e32 v245, v245
	v_lshlrev_b32_e32 v246, 16, v80
	v_and_b32_e32 v247, 0xffff0000, v80
	v_lshlrev_b32_e32 v248, 16, v81
	v_and_b32_e32 v249, 0xffff0000, v81
	v_pk_mul_f32 v[242:243], v[242:243], v[246:247]
	v_pk_mul_f32 v[244:245], v[244:245], v[248:249]
	v_cvt_pk_bf16_f32 v250, v242, v243
	v_cvt_pk_bf16_f32 v251, v244, v245
	global_store_dwordx2 v[104:105], v[250:251], off
	v_pk_add_f32 v[242:243], v[88:89], v[238:239]
	v_pk_add_f32 v[244:245], v[90:91], v[240:241]
	v_mul_f32_e32 v242, 0xbfb8aa3b, v242
	v_mul_f32_e32 v243, 0xbfb8aa3b, v243
	v_mul_f32_e32 v244, 0xbfb8aa3b, v244
	v_mul_f32_e32 v245, 0xbfb8aa3b, v245
	v_exp_f32_e32 v242, v242
	v_exp_f32_e32 v243, v243
	v_exp_f32_e32 v244, v244
	v_exp_f32_e32 v245, v245
	v_add_f32_e32 v242, 1.0, v242
	v_add_f32_e32 v243, 1.0, v243
	v_add_f32_e32 v244, 1.0, v244
	v_add_f32_e32 v245, 1.0, v245
	v_rcp_f32_e32 v242, v242
	v_rcp_f32_e32 v243, v243
	v_rcp_f32_e32 v244, v244
	v_rcp_f32_e32 v245, v245
	v_lshlrev_b32_e32 v246, 16, v82
	v_and_b32_e32 v247, 0xffff0000, v82
	v_lshlrev_b32_e32 v248, 16, v83
	v_and_b32_e32 v249, 0xffff0000, v83
	v_pk_mul_f32 v[242:243], v[242:243], v[246:247]
	v_pk_mul_f32 v[244:245], v[244:245], v[248:249]
	v_cvt_pk_bf16_f32 v250, v242, v243
	v_cvt_pk_bf16_f32 v251, v244, v245
	global_store_dwordx2 v[104:105], v[250:251], off offset:32
	v_mfma_f32_16x16x32_bf16 v[92:95], v[106:109], v[48:51], 0
	v_mfma_f32_16x16x32_bf16 v[96:99], v[152:155], v[48:51], 0
	v_mfma_f32_16x16x32_bf16 v[92:95], v[110:113], v[52:55], v[92:95]
	v_mfma_f32_16x16x32_bf16 v[96:99], v[160:163], v[52:55], v[96:99]
	v_mfma_f32_16x16x32_bf16 v[92:95], v[114:117], v[56:59], v[92:95]
	v_mfma_f32_16x16x32_bf16 v[96:99], v[164:167], v[56:59], v[96:99]
	v_mfma_f32_16x16x32_bf16 v[92:95], v[118:121], v[60:63], v[92:95]
	v_mfma_f32_16x16x32_bf16 v[96:99], v[184:187], v[60:63], v[96:99]
	v_mfma_f32_16x16x32_bf16 v[92:95], v[122:125], v[64:67], v[92:95]
	v_mfma_f32_16x16x32_bf16 v[96:99], v[188:191], v[64:67], v[96:99]
	v_mfma_f32_16x16x32_bf16 v[92:95], v[126:129], v[68:71], v[92:95]
	v_mfma_f32_16x16x32_bf16 v[96:99], v[222:225], v[68:71], v[96:99]
	v_mfma_f32_16x16x32_bf16 v[92:95], v[130:133], v[72:75], v[92:95]
	v_mfma_f32_16x16x32_bf16 v[96:99], v[226:229], v[72:75], v[96:99]
	v_mfma_f32_16x16x32_bf16 v[92:95], v[148:151], v[76:79], v[92:95]
	v_mfma_f32_16x16x32_bf16 v[96:99], v[230:233], v[76:79], v[96:99]
	ds_read_b64 v[80:81], v13 offset:8448
	ds_read_b64 v[82:83], v13 offset:8480
	ds_read_b128 v[48:51], v12 offset:25344
	ds_read_b128 v[52:55], v12 offset:25408
	ds_read_b128 v[56:59], v12 offset:25472
	ds_read_b128 v[60:63], v12 offset:25536
	ds_read_b128 v[64:67], v12 offset:25600
	ds_read_b128 v[68:71], v12 offset:25664
	ds_read_b128 v[72:75], v12 offset:25728
	ds_read_b128 v[76:79], v12 offset:25792
	s_waitcnt lgkmcnt(8)
; #define LAS __attribute__((address_space(3)))
; __device__ __forceinline__ float bflo(unsigned w) { return __uint_as_float(w << 16); }
; __device__ __forceinline__ float bfhi(unsigned w) { return __uint_as_float(w & 0xffff0000u); }
; __device__ __forceinline__ u32x2 pack4(const f32x4 a) { u32x2 v; v.x = cvt_pk_bf16(a[0], a[1]); v.y = cvt_pk_bf16(a[2], a[3]); return v; }
; __device__ __forceinline__ float sigmoidf_(float x) { return __builtin_amdgcn_rcpf(1.0f + __expf(-x)); }
; #define MFMA16(a, b, c) __builtin_amdgcn_mfma_f32_16x16x32_bf16((a), (b), (c), 0, 0, 0)
; __device__ void s5_c_unit(LAS unsigned char* lds, KP& P_, int l, int bc) {
;     ...
;         for (int i = 0; i < 8; ++i) { const int jt = jh * 8 + i; f32x4 acc = (f32x4){0.f, 0.f, 0.f, 0.f};
;             bf16x8 gc[8];
; #pragma unroll
;             for (int ks = 0; ks < 8; ++ks) gc[ks] = gn[ks];
;             if (i < 7) {
; #pragma unroll
;                 for (int ks = 0; ks < 8; ++ks) gn[ks] = *(const bf16x8*)(glut + (size_t)((jt + 1) * 16 + fr) * 256 + ks * 32 + fq * 8); }
; #pragma unroll
;             for (int ks = 0; ks < 8; ++ks) acc = MFMA16(gc[ks], yf[ks], acc);
;             const int jc = jt * 16 + fq * 4; const u32x2 yraw = *(const LAS u32x2*)(YG + tq * 264 + jc); const float yv[4] = {bflo(yraw.x), bfhi(yraw.x), bflo(yraw.y), bfhi(yraw.y)}; f32x4 r;
; #pragma unroll
;             for (int j = 0; j < 4; ++j) r[j] = yv[j] * sigmoidf_(acc[j] + gbv[i][j]);
;             *(u32x2*)(mixed + ((size_t)bc * 64 + tq) * DM + 768 + jc) = pack4(r); }
	s_nop 7
	v_lshl_add_u64 v[104:105], v[104:105], 0, s[14:15]
	v_pk_add_f32 v[242:243], v[92:93], v[234:235]
	v_pk_add_f32 v[244:245], v[94:95], v[236:237]
	v_mul_f32_e32 v242, 0xbfb8aa3b, v242
	v_mul_f32_e32 v243, 0xbfb8aa3b, v243
	v_mul_f32_e32 v244, 0xbfb8aa3b, v244
	v_mul_f32_e32 v245, 0xbfb8aa3b, v245
	v_exp_f32_e32 v242, v242
	v_exp_f32_e32 v243, v243
	v_exp_f32_e32 v244, v244
	v_exp_f32_e32 v245, v245
	v_add_f32_e32 v242, 1.0, v242
	v_add_f32_e32 v243, 1.0, v243
	v_add_f32_e32 v244, 1.0, v244
	v_add_f32_e32 v245, 1.0, v245
	v_rcp_f32_e32 v242, v242
	v_rcp_f32_e32 v243, v243
	v_rcp_f32_e32 v244, v244
	v_rcp_f32_e32 v245, v245
	v_lshlrev_b32_e32 v246, 16, v80
	v_and_b32_e32 v247, 0xffff0000, v80
	v_lshlrev_b32_e32 v248, 16, v81
	v_and_b32_e32 v249, 0xffff0000, v81
	v_pk_mul_f32 v[242:243], v[242:243], v[246:247]
	v_pk_mul_f32 v[244:245], v[244:245], v[248:249]
	v_cvt_pk_bf16_f32 v250, v242, v243
	v_cvt_pk_bf16_f32 v251, v244, v245
	global_store_dwordx2 v[104:105], v[250:251], off
	v_pk_add_f32 v[242:243], v[96:97], v[238:239]
	v_pk_add_f32 v[244:245], v[98:99], v[240:241]
	v_mul_f32_e32 v242, 0xbfb8aa3b, v242
	v_mul_f32_e32 v243, 0xbfb8aa3b, v243
	v_mul_f32_e32 v244, 0xbfb8aa3b, v244
	v_mul_f32_e32 v245, 0xbfb8aa3b, v245
	v_exp_f32_e32 v242, v242
	v_exp_f32_e32 v243, v243
	v_exp_f32_e32 v244, v244
	v_exp_f32_e32 v245, v245
	v_add_f32_e32 v242, 1.0, v242
	v_add_f32_e32 v243, 1.0, v243
	v_add_f32_e32 v244, 1.0, v244
	v_add_f32_e32 v245, 1.0, v245
	v_rcp_f32_e32 v242, v242
	v_rcp_f32_e32 v243, v243
	v_rcp_f32_e32 v244, v244
	v_rcp_f32_e32 v245, v245
	v_lshlrev_b32_e32 v246, 16, v82
	v_and_b32_e32 v247, 0xffff0000, v82
	v_lshlrev_b32_e32 v248, 16, v83
	v_and_b32_e32 v249, 0xffff0000, v83
	v_pk_mul_f32 v[242:243], v[242:243], v[246:247]
	v_pk_mul_f32 v[244:245], v[244:245], v[248:249]
	v_cvt_pk_bf16_f32 v250, v242, v243
	v_cvt_pk_bf16_f32 v251, v244, v245
	global_store_dwordx2 v[104:105], v[250:251], off offset:32
	v_mfma_f32_16x16x32_bf16 v[84:87], v[106:109], v[16:19], 0
	v_mfma_f32_16x16x32_bf16 v[88:91], v[152:155], v[16:19], 0
	v_mfma_f32_16x16x32_bf16 v[84:87], v[110:113], v[20:23], v[84:87]
	v_mfma_f32_16x16x32_bf16 v[88:91], v[160:163], v[20:23], v[88:91]
	v_mfma_f32_16x16x32_bf16 v[84:87], v[114:117], v[24:27], v[84:87]
	v_mfma_f32_16x16x32_bf16 v[88:91], v[164:167], v[24:27], v[88:91]
	v_mfma_f32_16x16x32_bf16 v[84:87], v[118:121], v[28:31], v[84:87]
	v_mfma_f32_16x16x32_bf16 v[88:91], v[184:187], v[28:31], v[88:91]
	v_mfma_f32_16x16x32_bf16 v[84:87], v[122:125], v[32:35], v[84:87]
	v_mfma_f32_16x16x32_bf16 v[88:91], v[188:191], v[32:35], v[88:91]
	v_mfma_f32_16x16x32_bf16 v[84:87], v[126:129], v[36:39], v[84:87]
	v_mfma_f32_16x16x32_bf16 v[88:91], v[222:225], v[36:39], v[88:91]
	v_mfma_f32_16x16x32_bf16 v[84:87], v[130:133], v[40:43], v[84:87]
	v_mfma_f32_16x16x32_bf16 v[88:91], v[226:229], v[40:43], v[88:91]
	v_mfma_f32_16x16x32_bf16 v[84:87], v[148:151], v[44:47], v[84:87]
	v_mfma_f32_16x16x32_bf16 v[88:91], v[230:233], v[44:47], v[88:91]
	ds_read_b64 v[80:81], v13 offset:16896
	ds_read_b64 v[82:83], v13 offset:16928
	s_waitcnt lgkmcnt(0)
; #define LAS __attribute__((address_space(3)))
; __device__ __forceinline__ float bflo(unsigned w) { return __uint_as_float(w << 16); }
; __device__ __forceinline__ float bfhi(unsigned w) { return __uint_as_float(w & 0xffff0000u); }
; __device__ __forceinline__ u32x2 pack4(const f32x4 a) { u32x2 v; v.x = cvt_pk_bf16(a[0], a[1]); v.y = cvt_pk_bf16(a[2], a[3]); return v; }
; __device__ __forceinline__ float sigmoidf_(float x) { return __builtin_amdgcn_rcpf(1.0f + __expf(-x)); }
; #define MFMA16(a, b, c) __builtin_amdgcn_mfma_f32_16x16x32_bf16((a), (b), (c), 0, 0, 0)
; __device__ void s5_c_unit(LAS unsigned char* lds, KP& P_, int l, int bc) {
;     ...
;         for (int i = 0; i < 8; ++i) { const int jt = jh * 8 + i; f32x4 acc = (f32x4){0.f, 0.f, 0.f, 0.f};
;             bf16x8 gc[8];
; #pragma unroll
;             for (int ks = 0; ks < 8; ++ks) gc[ks] = gn[ks];
;             if (i < 7) {
; #pragma unroll
;                 for (int ks = 0; ks < 8; ++ks) gn[ks] = *(const bf16x8*)(glut + (size_t)((jt + 1) * 16 + fr) * 256 + ks * 32 + fq * 8); }
; #pragma unroll
;             for (int ks = 0; ks < 8; ++ks) acc = MFMA16(gc[ks], yf[ks], acc);
;             const int jc = jt * 16 + fq * 4; const u32x2 yraw = *(const LAS u32x2*)(YG + tq * 264 + jc); const float yv[4] = {bflo(yraw.x), bfhi(yraw.x), bflo(yraw.y), bfhi(yraw.y)}; f32x4 r;
; #pragma unroll
;             for (int j = 0; j < 4; ++j) r[j] = yv[j] * sigmoidf_(acc[j] + gbv[i][j]);
;             *(u32x2*)(mixed + ((size_t)bc * 64 + tq) * DM + 768 + jc) = pack4(r); }
	s_nop 7
	v_lshl_add_u64 v[104:105], v[104:105], 0, s[14:15]
	v_pk_add_f32 v[242:243], v[84:85], v[234:235]
	v_pk_add_f32 v[244:245], v[86:87], v[236:237]
	v_mul_f32_e32 v242, 0xbfb8aa3b, v242
	v_mul_f32_e32 v243, 0xbfb8aa3b, v243
	v_mul_f32_e32 v244, 0xbfb8aa3b, v244
	v_mul_f32_e32 v245, 0xbfb8aa3b, v245
	v_exp_f32_e32 v242, v242
	v_exp_f32_e32 v243, v243
	v_exp_f32_e32 v244, v244
	v_exp_f32_e32 v245, v245
	v_add_f32_e32 v242, 1.0, v242
	v_add_f32_e32 v243, 1.0, v243
	v_add_f32_e32 v244, 1.0, v244
	v_add_f32_e32 v245, 1.0, v245
	v_rcp_f32_e32 v242, v242
	v_rcp_f32_e32 v243, v243
	v_rcp_f32_e32 v244, v244
	v_rcp_f32_e32 v245, v245
	v_lshlrev_b32_e32 v246, 16, v80
	v_and_b32_e32 v247, 0xffff0000, v80
	v_lshlrev_b32_e32 v248, 16, v81
	v_and_b32_e32 v249, 0xffff0000, v81
	v_pk_mul_f32 v[242:243], v[242:243], v[246:247]
	v_pk_mul_f32 v[244:245], v[244:245], v[248:249]
	v_cvt_pk_bf16_f32 v250, v242, v243
	v_cvt_pk_bf16_f32 v251, v244, v245
	global_store_dwordx2 v[104:105], v[250:251], off
	v_pk_add_f32 v[242:243], v[88:89], v[238:239]
	v_pk_add_f32 v[244:245], v[90:91], v[240:241]
	v_mul_f32_e32 v242, 0xbfb8aa3b, v242
	v_mul_f32_e32 v243, 0xbfb8aa3b, v243
	v_mul_f32_e32 v244, 0xbfb8aa3b, v244
	v_mul_f32_e32 v245, 0xbfb8aa3b, v245
	v_exp_f32_e32 v242, v242
	v_exp_f32_e32 v243, v243
	v_exp_f32_e32 v244, v244
	v_exp_f32_e32 v245, v245
	v_add_f32_e32 v242, 1.0, v242
	v_add_f32_e32 v243, 1.0, v243
	v_add_f32_e32 v244, 1.0, v244
	v_add_f32_e32 v245, 1.0, v245
	v_rcp_f32_e32 v242, v242
	v_rcp_f32_e32 v243, v243
	v_rcp_f32_e32 v244, v244
	v_rcp_f32_e32 v245, v245
	v_lshlrev_b32_e32 v246, 16, v82
	v_and_b32_e32 v247, 0xffff0000, v82
	v_lshlrev_b32_e32 v248, 16, v83
	v_and_b32_e32 v249, 0xffff0000, v83
	v_pk_mul_f32 v[242:243], v[242:243], v[246:247]
	v_pk_mul_f32 v[244:245], v[244:245], v[248:249]
	v_cvt_pk_bf16_f32 v250, v242, v243
	v_cvt_pk_bf16_f32 v251, v244, v245
	global_store_dwordx2 v[104:105], v[250:251], off offset:32
	v_mfma_f32_16x16x32_bf16 v[92:95], v[106:109], v[48:51], 0
	v_mfma_f32_16x16x32_bf16 v[96:99], v[152:155], v[48:51], 0
	v_mfma_f32_16x16x32_bf16 v[92:95], v[110:113], v[52:55], v[92:95]
	v_mfma_f32_16x16x32_bf16 v[96:99], v[160:163], v[52:55], v[96:99]
	v_mfma_f32_16x16x32_bf16 v[92:95], v[114:117], v[56:59], v[92:95]
	v_mfma_f32_16x16x32_bf16 v[96:99], v[164:167], v[56:59], v[96:99]
	v_mfma_f32_16x16x32_bf16 v[92:95], v[118:121], v[60:63], v[92:95]
	v_mfma_f32_16x16x32_bf16 v[96:99], v[184:187], v[60:63], v[96:99]
	v_mfma_f32_16x16x32_bf16 v[92:95], v[122:125], v[64:67], v[92:95]
	v_mfma_f32_16x16x32_bf16 v[96:99], v[188:191], v[64:67], v[96:99]
	v_mfma_f32_16x16x32_bf16 v[92:95], v[126:129], v[68:71], v[92:95]
	v_mfma_f32_16x16x32_bf16 v[96:99], v[222:225], v[68:71], v[96:99]
	v_mfma_f32_16x16x32_bf16 v[92:95], v[130:133], v[72:75], v[92:95]
	v_mfma_f32_16x16x32_bf16 v[96:99], v[226:229], v[72:75], v[96:99]
	v_mfma_f32_16x16x32_bf16 v[92:95], v[148:151], v[76:79], v[92:95]
	v_mfma_f32_16x16x32_bf16 v[96:99], v[230:233], v[76:79], v[96:99]
	ds_read_b64 v[80:81], v13 offset:25344
	ds_read_b64 v[82:83], v13 offset:25376
	s_waitcnt lgkmcnt(0)
	s_nop 7
	v_lshl_add_u64 v[104:105], v[104:105], 0, s[14:15]
	v_pk_add_f32 v[242:243], v[92:93], v[234:235]
	v_pk_add_f32 v[244:245], v[94:95], v[236:237]
	v_mul_f32_e32 v242, 0xbfb8aa3b, v242
	v_mul_f32_e32 v243, 0xbfb8aa3b, v243
	v_mul_f32_e32 v244, 0xbfb8aa3b, v244
	v_mul_f32_e32 v245, 0xbfb8aa3b, v245
	v_exp_f32_e32 v242, v242
	v_exp_f32_e32 v243, v243
	v_exp_f32_e32 v244, v244
	v_exp_f32_e32 v245, v245
	v_add_f32_e32 v242, 1.0, v242
	v_add_f32_e32 v243, 1.0, v243
	v_add_f32_e32 v244, 1.0, v244
	v_add_f32_e32 v245, 1.0, v245
	v_rcp_f32_e32 v242, v242
	v_rcp_f32_e32 v243, v243
	v_rcp_f32_e32 v244, v244
	v_rcp_f32_e32 v245, v245
	v_lshlrev_b32_e32 v246, 16, v80
	v_and_b32_e32 v247, 0xffff0000, v80
	v_lshlrev_b32_e32 v248, 16, v81
	v_and_b32_e32 v249, 0xffff0000, v81
	v_pk_mul_f32 v[242:243], v[242:243], v[246:247]
	v_pk_mul_f32 v[244:245], v[244:245], v[248:249]
	v_cvt_pk_bf16_f32 v250, v242, v243
	v_cvt_pk_bf16_f32 v251, v244, v245
	global_store_dwordx2 v[104:105], v[250:251], off
	v_pk_add_f32 v[242:243], v[96:97], v[238:239]
	v_pk_add_f32 v[244:245], v[98:99], v[240:241]
	v_mul_f32_e32 v242, 0xbfb8aa3b, v242
	v_mul_f32_e32 v243, 0xbfb8aa3b, v243
	v_mul_f32_e32 v244, 0xbfb8aa3b, v244
	v_mul_f32_e32 v245, 0xbfb8aa3b, v245
	v_exp_f32_e32 v242, v242
	v_exp_f32_e32 v243, v243
	v_exp_f32_e32 v244, v244
	v_exp_f32_e32 v245, v245
	v_add_f32_e32 v242, 1.0, v242
	v_add_f32_e32 v243, 1.0, v243
	v_add_f32_e32 v244, 1.0, v244
	v_add_f32_e32 v245, 1.0, v245
	v_rcp_f32_e32 v242, v242
	v_rcp_f32_e32 v243, v243
	v_rcp_f32_e32 v244, v244
	v_rcp_f32_e32 v245, v245
	v_lshlrev_b32_e32 v246, 16, v82
	v_and_b32_e32 v247, 0xffff0000, v82
	v_lshlrev_b32_e32 v248, 16, v83
	v_and_b32_e32 v249, 0xffff0000, v83
	v_pk_mul_f32 v[242:243], v[242:243], v[246:247]
	v_pk_mul_f32 v[244:245], v[244:245], v[248:249]
	v_cvt_pk_bf16_f32 v250, v242, v243
	v_cvt_pk_bf16_f32 v251, v244, v245
	global_store_dwordx2 v[104:105], v[250:251], off offset:32
	s_mov_b64 s[6:7], 0
	s_waitcnt lgkmcnt(0)
	s_barrier
